# v13 + in_proj tile schedule: second column tile swapped between the two workgroup groups (q,z_attn,u)/(k,v,z_ssm) to balance epilogue cost
# speedup vs baseline: 1.0012x; 1.0012x over previous
;     __device__ bool next(int i, Unit& u) const {
;         const int L = i * G + c; if (L >= nwg) return false;
;         int wgid = L; { constexpr int q = nwg / NXCD, r = nwg % NXCD; const int xcd = wgid % NXCD, off = wgid / NXCD; wgid = (xcd < r ? xcd * (q + 1) : r * (q + 1) + (xcd - r) * q) + off; }
;         constexpr int nig = WGM * nN; const int gid = wgid / nig, fm = gid * WGM, gsz = (nM - fm) < WGM ? (nM - fm) : WGM;
;         u.pm = fm + ((wgid % nig) % gsz); u.pn = (wgid % nig) / gsz; return true;
.LBB0_186:
	s_add_i32 s50, s50, 1
	s_lshl_b32 s27, s50, 8
	s_add_i32 s27, s27, s2
	s_cmpk_lt_i32 s27, 0x300
	s_cselect_b64 s[30:31], -1, 0
	s_cmpk_gt_i32 s27, 0x2ff
	s_cbranch_scc1 .LBB0_188
	s_ashr_i32 s26, s27, 31
	s_lshr_b32 s26, s26, 29
	s_add_i32 s26, s27, s26
	s_ashr_i32 s28, s26, 3
	s_and_b32 s26, s26, -8
	s_sub_i32 s26, s27, s26
	s_cmp_lt_i32 s26, 0
	s_cselect_b32 s27, s56, 0x60
	s_mul_i32 s26, s27, s26
	s_add_i32 s26, s26, s28
	s_mul_hi_i32 s27, s26, 0x2aaaaaab
	s_lshr_b32 s28, s27, 31
	s_ashr_i32 s27, s27, 4
	s_add_i32 s27, s27, s28
	s_lshl_b32 s28, s27, 3
	s_mulk_i32 s27, 0x60
	s_sub_i32 s26, s26, s27
	s_bfe_i32 s27, s26, 0x80000
	s_bfe_u32 s27, s27, 0x3000c
	s_add_i32 s27, s26, s27
	s_bfe_i32 s29, s27, 0x80000
	s_and_b32 s27, s27, 0xf8
	s_sub_i32 s26, s26, s27
	s_sext_i32_i16 s29, s29
	s_sext_i32_i8 s26, s26
	s_add_i32 s26, s28, s26
	s_ashr_i32 s28, s29, 3
	s_cmp_eq_u32 s50, 1
	s_cselect_b32 s98, 2, 0
	s_xor_b32 s28, s28, s98
